# sgemm_wide K loops fully unrolled with 32 loads in flight (was load-wait-mfma serialized)
# speedup vs baseline: 1.0031x; 1.0031x over previous
.LBB0_309:
	s_and_b32 s9, s5, 0xffffffc0
	v_add_u32_e32 v0, s9, v33
	v_ashrrev_i32_e32 v1, 31, v0
	s_lshl_b32 s9, s4, 11
	v_lshlrev_b64 v[0:1], 11, v[0:1]
	s_and_b32 s9, s9, 0x7c0000
	v_lshl_add_u64 v[20:21], s[88:89], 0, v[0:1]
	v_lshl_or_b32 v148, v34, 11, s9
	v_mov_b32_e32 v0, 0
	v_lshl_add_u64 v[22:23], s[2:3], 0, v[148:149]
	s_movk_i32 s9, 0xffe0
	v_mov_b32_e32 v1, v0
	v_mov_b32_e32 v2, v0
	v_mov_b32_e32 v3, v0
	v_mov_b32_e32 v4, v0
	v_mov_b32_e32 v5, v0
	v_mov_b32_e32 v6, v0
	v_mov_b32_e32 v7, v0
	v_mov_b32_e32 v8, v0
	v_mov_b32_e32 v9, v0
	v_mov_b32_e32 v10, v0
	v_mov_b32_e32 v11, v0
	v_mov_b32_e32 v12, v0
	v_mov_b32_e32 v13, v0
	v_mov_b32_e32 v14, v0
	v_mov_b32_e32 v15, v0
	v_lshl_add_u64 v[24:25], v[20:21], 0, v[18:19]
	v_add_co_u32_e32 v30, vcc, s7, v24
	s_nop 1
	v_addc_co_u32_e32 v31, vcc, 0, v25, vcc
	v_add_co_u32_e32 v24, vcc, s30, v24
	s_nop 1
	v_addc_co_u32_e32 v25, vcc, 0, v25, vcc
	v_lshl_add_u64 v[26:27], v[22:23], 0, v[18:19]
	s_mov_b32 s10, 0x8000
	v_add_co_u32_e32 v28, vcc, s10, v26
	s_nop 1
	v_addc_co_u32_e32 v29, vcc, 0, v27, vcc
	global_load_dwordx4 v[62:65], v[30:31], off
	global_load_dwordx4 v[94:97], v[26:27], off
	global_load_dwordx4 v[188:191], v[28:29], off
	global_load_dwordx4 v[220:223], v[24:25], off
	global_load_dwordx4 v[66:69], v[30:31], off offset:64
	global_load_dwordx4 v[98:101], v[26:27], off offset:64
	global_load_dwordx4 v[192:195], v[28:29], off offset:64
	global_load_dwordx4 v[224:227], v[24:25], off offset:64
	global_load_dwordx4 v[70:73], v[30:31], off offset:128
	global_load_dwordx4 v[102:105], v[26:27], off offset:128
	global_load_dwordx4 v[196:199], v[28:29], off offset:128
	global_load_dwordx4 v[228:231], v[24:25], off offset:128
	global_load_dwordx4 v[74:77], v[30:31], off offset:192
	global_load_dwordx4 v[106:109], v[26:27], off offset:192
	global_load_dwordx4 v[200:203], v[28:29], off offset:192
	global_load_dwordx4 v[232:235], v[24:25], off offset:192
	global_load_dwordx4 v[78:81], v[30:31], off offset:256
	global_load_dwordx4 v[110:113], v[26:27], off offset:256
	global_load_dwordx4 v[204:207], v[28:29], off offset:256
	global_load_dwordx4 v[162:165], v[24:25], off offset:256
	global_load_dwordx4 v[82:85], v[30:31], off offset:320
	global_load_dwordx4 v[114:117], v[26:27], off offset:320
	global_load_dwordx4 v[208:211], v[28:29], off offset:320
	global_load_dwordx4 v[166:169], v[24:25], off offset:320
	global_load_dwordx4 v[86:89], v[30:31], off offset:384
	global_load_dwordx4 v[118:121], v[26:27], off offset:384
	global_load_dwordx4 v[212:215], v[28:29], off offset:384
	global_load_dwordx4 v[170:173], v[24:25], off offset:384
	global_load_dwordx4 v[90:93], v[30:31], off offset:448
	global_load_dwordx4 v[122:125], v[26:27], off offset:448
	global_load_dwordx4 v[216:219], v[28:29], off offset:448
	global_load_dwordx4 v[236:239], v[24:25], off offset:448
	s_waitcnt vmcnt(28)
	v_mfma_f32_16x16x32_bf16 v[12:15], v[94:97], v[62:65], v[12:15]
	v_mfma_f32_16x16x32_bf16 v[8:11], v[188:191], v[62:65], v[8:11]
	v_mfma_f32_16x16x32_bf16 v[4:7], v[94:97], v[220:223], v[4:7]
	v_mfma_f32_16x16x32_bf16 v[0:3], v[188:191], v[220:223], v[0:3]
	global_load_dwordx4 v[62:65], v[30:31], off offset:512
	global_load_dwordx4 v[94:97], v[26:27], off offset:512
	global_load_dwordx4 v[188:191], v[28:29], off offset:512
	global_load_dwordx4 v[220:223], v[24:25], off offset:512
	s_waitcnt vmcnt(28)
	v_mfma_f32_16x16x32_bf16 v[12:15], v[98:101], v[66:69], v[12:15]
	v_mfma_f32_16x16x32_bf16 v[8:11], v[192:195], v[66:69], v[8:11]
	v_mfma_f32_16x16x32_bf16 v[4:7], v[98:101], v[224:227], v[4:7]
	v_mfma_f32_16x16x32_bf16 v[0:3], v[192:195], v[224:227], v[0:3]
	global_load_dwordx4 v[66:69], v[30:31], off offset:576
	global_load_dwordx4 v[98:101], v[26:27], off offset:576
	global_load_dwordx4 v[192:195], v[28:29], off offset:576
	global_load_dwordx4 v[224:227], v[24:25], off offset:576
	s_waitcnt vmcnt(28)
	v_mfma_f32_16x16x32_bf16 v[12:15], v[102:105], v[70:73], v[12:15]
	v_mfma_f32_16x16x32_bf16 v[8:11], v[196:199], v[70:73], v[8:11]
	v_mfma_f32_16x16x32_bf16 v[4:7], v[102:105], v[228:231], v[4:7]
	v_mfma_f32_16x16x32_bf16 v[0:3], v[196:199], v[228:231], v[0:3]
	global_load_dwordx4 v[70:73], v[30:31], off offset:640
	global_load_dwordx4 v[102:105], v[26:27], off offset:640
	global_load_dwordx4 v[196:199], v[28:29], off offset:640
	global_load_dwordx4 v[228:231], v[24:25], off offset:640
	s_waitcnt vmcnt(28)
	v_mfma_f32_16x16x32_bf16 v[12:15], v[106:109], v[74:77], v[12:15]
	v_mfma_f32_16x16x32_bf16 v[8:11], v[200:203], v[74:77], v[8:11]
	v_mfma_f32_16x16x32_bf16 v[4:7], v[106:109], v[232:235], v[4:7]
	v_mfma_f32_16x16x32_bf16 v[0:3], v[200:203], v[232:235], v[0:3]
	global_load_dwordx4 v[74:77], v[30:31], off offset:704
	global_load_dwordx4 v[106:109], v[26:27], off offset:704
	global_load_dwordx4 v[200:203], v[28:29], off offset:704
	global_load_dwordx4 v[232:235], v[24:25], off offset:704
	s_waitcnt vmcnt(28)
	v_mfma_f32_16x16x32_bf16 v[12:15], v[110:113], v[78:81], v[12:15]
	v_mfma_f32_16x16x32_bf16 v[8:11], v[204:207], v[78:81], v[8:11]
	v_mfma_f32_16x16x32_bf16 v[4:7], v[110:113], v[162:165], v[4:7]
	v_mfma_f32_16x16x32_bf16 v[0:3], v[204:207], v[162:165], v[0:3]
	global_load_dwordx4 v[78:81], v[30:31], off offset:768
	global_load_dwordx4 v[110:113], v[26:27], off offset:768
	global_load_dwordx4 v[204:207], v[28:29], off offset:768
	global_load_dwordx4 v[162:165], v[24:25], off offset:768
	s_waitcnt vmcnt(28)
	v_mfma_f32_16x16x32_bf16 v[12:15], v[114:117], v[82:85], v[12:15]
	v_mfma_f32_16x16x32_bf16 v[8:11], v[208:211], v[82:85], v[8:11]
	v_mfma_f32_16x16x32_bf16 v[4:7], v[114:117], v[166:169], v[4:7]
	v_mfma_f32_16x16x32_bf16 v[0:3], v[208:211], v[166:169], v[0:3]
	global_load_dwordx4 v[82:85], v[30:31], off offset:832
	global_load_dwordx4 v[114:117], v[26:27], off offset:832
	global_load_dwordx4 v[208:211], v[28:29], off offset:832
	global_load_dwordx4 v[166:169], v[24:25], off offset:832
	s_waitcnt vmcnt(28)
	v_mfma_f32_16x16x32_bf16 v[12:15], v[118:121], v[86:89], v[12:15]
	v_mfma_f32_16x16x32_bf16 v[8:11], v[212:215], v[86:89], v[8:11]
	v_mfma_f32_16x16x32_bf16 v[4:7], v[118:121], v[170:173], v[4:7]
	v_mfma_f32_16x16x32_bf16 v[0:3], v[212:215], v[170:173], v[0:3]
	global_load_dwordx4 v[86:89], v[30:31], off offset:896
	global_load_dwordx4 v[118:121], v[26:27], off offset:896
	global_load_dwordx4 v[212:215], v[28:29], off offset:896
	global_load_dwordx4 v[170:173], v[24:25], off offset:896
	s_waitcnt vmcnt(28)
	v_mfma_f32_16x16x32_bf16 v[12:15], v[122:125], v[90:93], v[12:15]
	v_mfma_f32_16x16x32_bf16 v[8:11], v[216:219], v[90:93], v[8:11]
	v_mfma_f32_16x16x32_bf16 v[4:7], v[122:125], v[236:239], v[4:7]
	v_mfma_f32_16x16x32_bf16 v[0:3], v[216:219], v[236:239], v[0:3]
	global_load_dwordx4 v[90:93], v[30:31], off offset:960
	global_load_dwordx4 v[122:125], v[26:27], off offset:960
	global_load_dwordx4 v[216:219], v[28:29], off offset:960
	global_load_dwordx4 v[236:239], v[24:25], off offset:960
	s_waitcnt vmcnt(28)
	v_mfma_f32_16x16x32_bf16 v[12:15], v[94:97], v[62:65], v[12:15]
	v_mfma_f32_16x16x32_bf16 v[8:11], v[188:191], v[62:65], v[8:11]
	v_mfma_f32_16x16x32_bf16 v[4:7], v[94:97], v[220:223], v[4:7]
	v_mfma_f32_16x16x32_bf16 v[0:3], v[188:191], v[220:223], v[0:3]
	global_load_dwordx4 v[62:65], v[30:31], off offset:1024
	global_load_dwordx4 v[94:97], v[26:27], off offset:1024
	global_load_dwordx4 v[188:191], v[28:29], off offset:1024
	global_load_dwordx4 v[220:223], v[24:25], off offset:1024
	s_waitcnt vmcnt(28)
	v_mfma_f32_16x16x32_bf16 v[12:15], v[98:101], v[66:69], v[12:15]
	v_mfma_f32_16x16x32_bf16 v[8:11], v[192:195], v[66:69], v[8:11]
	v_mfma_f32_16x16x32_bf16 v[4:7], v[98:101], v[224:227], v[4:7]
	v_mfma_f32_16x16x32_bf16 v[0:3], v[192:195], v[224:227], v[0:3]
	global_load_dwordx4 v[66:69], v[30:31], off offset:1088
	global_load_dwordx4 v[98:101], v[26:27], off offset:1088
	global_load_dwordx4 v[192:195], v[28:29], off offset:1088
	global_load_dwordx4 v[224:227], v[24:25], off offset:1088
	s_waitcnt vmcnt(28)
	v_mfma_f32_16x16x32_bf16 v[12:15], v[102:105], v[70:73], v[12:15]
	v_mfma_f32_16x16x32_bf16 v[8:11], v[196:199], v[70:73], v[8:11]
	v_mfma_f32_16x16x32_bf16 v[4:7], v[102:105], v[228:231], v[4:7]
	v_mfma_f32_16x16x32_bf16 v[0:3], v[196:199], v[228:231], v[0:3]
	global_load_dwordx4 v[70:73], v[30:31], off offset:1152
	global_load_dwordx4 v[102:105], v[26:27], off offset:1152
	global_load_dwordx4 v[196:199], v[28:29], off offset:1152
	global_load_dwordx4 v[228:231], v[24:25], off offset:1152
	s_waitcnt vmcnt(28)
	v_mfma_f32_16x16x32_bf16 v[12:15], v[106:109], v[74:77], v[12:15]
	v_mfma_f32_16x16x32_bf16 v[8:11], v[200:203], v[74:77], v[8:11]
	v_mfma_f32_16x16x32_bf16 v[4:7], v[106:109], v[232:235], v[4:7]
	v_mfma_f32_16x16x32_bf16 v[0:3], v[200:203], v[232:235], v[0:3]
	global_load_dwordx4 v[74:77], v[30:31], off offset:1216
	global_load_dwordx4 v[106:109], v[26:27], off offset:1216
	global_load_dwordx4 v[200:203], v[28:29], off offset:1216
	global_load_dwordx4 v[232:235], v[24:25], off offset:1216
	s_waitcnt vmcnt(28)
	v_mfma_f32_16x16x32_bf16 v[12:15], v[110:113], v[78:81], v[12:15]
	v_mfma_f32_16x16x32_bf16 v[8:11], v[204:207], v[78:81], v[8:11]
	v_mfma_f32_16x16x32_bf16 v[4:7], v[110:113], v[162:165], v[4:7]
	v_mfma_f32_16x16x32_bf16 v[0:3], v[204:207], v[162:165], v[0:3]
	global_load_dwordx4 v[78:81], v[30:31], off offset:1280
	global_load_dwordx4 v[110:113], v[26:27], off offset:1280
	global_load_dwordx4 v[204:207], v[28:29], off offset:1280
	global_load_dwordx4 v[162:165], v[24:25], off offset:1280
	s_waitcnt vmcnt(28)
	v_mfma_f32_16x16x32_bf16 v[12:15], v[114:117], v[82:85], v[12:15]
	v_mfma_f32_16x16x32_bf16 v[8:11], v[208:211], v[82:85], v[8:11]
	v_mfma_f32_16x16x32_bf16 v[4:7], v[114:117], v[166:169], v[4:7]
	v_mfma_f32_16x16x32_bf16 v[0:3], v[208:211], v[166:169], v[0:3]
	global_load_dwordx4 v[82:85], v[30:31], off offset:1344
	global_load_dwordx4 v[114:117], v[26:27], off offset:1344
	global_load_dwordx4 v[208:211], v[28:29], off offset:1344
	global_load_dwordx4 v[166:169], v[24:25], off offset:1344
	s_waitcnt vmcnt(28)
	v_mfma_f32_16x16x32_bf16 v[12:15], v[118:121], v[86:89], v[12:15]
	v_mfma_f32_16x16x32_bf16 v[8:11], v[212:215], v[86:89], v[8:11]
	v_mfma_f32_16x16x32_bf16 v[4:7], v[118:121], v[170:173], v[4:7]
	v_mfma_f32_16x16x32_bf16 v[0:3], v[212:215], v[170:173], v[0:3]
	global_load_dwordx4 v[86:89], v[30:31], off offset:1408
	global_load_dwordx4 v[118:121], v[26:27], off offset:1408
	global_load_dwordx4 v[212:215], v[28:29], off offset:1408
	global_load_dwordx4 v[170:173], v[24:25], off offset:1408
	s_waitcnt vmcnt(28)
	v_mfma_f32_16x16x32_bf16 v[12:15], v[122:125], v[90:93], v[12:15]
	v_mfma_f32_16x16x32_bf16 v[8:11], v[216:219], v[90:93], v[8:11]
	v_mfma_f32_16x16x32_bf16 v[4:7], v[122:125], v[236:239], v[4:7]
	v_mfma_f32_16x16x32_bf16 v[0:3], v[216:219], v[236:239], v[0:3]
	global_load_dwordx4 v[90:93], v[30:31], off offset:1472
	global_load_dwordx4 v[122:125], v[26:27], off offset:1472
	global_load_dwordx4 v[216:219], v[28:29], off offset:1472
	global_load_dwordx4 v[236:239], v[24:25], off offset:1472
	s_waitcnt vmcnt(28)
	v_mfma_f32_16x16x32_bf16 v[12:15], v[94:97], v[62:65], v[12:15]
	v_mfma_f32_16x16x32_bf16 v[8:11], v[188:191], v[62:65], v[8:11]
	v_mfma_f32_16x16x32_bf16 v[4:7], v[94:97], v[220:223], v[4:7]
	v_mfma_f32_16x16x32_bf16 v[0:3], v[188:191], v[220:223], v[0:3]
	global_load_dwordx4 v[62:65], v[30:31], off offset:1536
	global_load_dwordx4 v[94:97], v[26:27], off offset:1536
	global_load_dwordx4 v[188:191], v[28:29], off offset:1536
	global_load_dwordx4 v[220:223], v[24:25], off offset:1536
	s_waitcnt vmcnt(28)
	v_mfma_f32_16x16x32_bf16 v[12:15], v[98:101], v[66:69], v[12:15]
	v_mfma_f32_16x16x32_bf16 v[8:11], v[192:195], v[66:69], v[8:11]
	v_mfma_f32_16x16x32_bf16 v[4:7], v[98:101], v[224:227], v[4:7]
	v_mfma_f32_16x16x32_bf16 v[0:3], v[192:195], v[224:227], v[0:3]
	global_load_dwordx4 v[66:69], v[30:31], off offset:1600
	global_load_dwordx4 v[98:101], v[26:27], off offset:1600
	global_load_dwordx4 v[192:195], v[28:29], off offset:1600
	global_load_dwordx4 v[224:227], v[24:25], off offset:1600
	s_waitcnt vmcnt(28)
	v_mfma_f32_16x16x32_bf16 v[12:15], v[102:105], v[70:73], v[12:15]
	v_mfma_f32_16x16x32_bf16 v[8:11], v[196:199], v[70:73], v[8:11]
	v_mfma_f32_16x16x32_bf16 v[4:7], v[102:105], v[228:231], v[4:7]
	v_mfma_f32_16x16x32_bf16 v[0:3], v[196:199], v[228:231], v[0:3]
	global_load_dwordx4 v[70:73], v[30:31], off offset:1664
	global_load_dwordx4 v[102:105], v[26:27], off offset:1664
	global_load_dwordx4 v[196:199], v[28:29], off offset:1664
	global_load_dwordx4 v[228:231], v[24:25], off offset:1664
	s_waitcnt vmcnt(28)
	v_mfma_f32_16x16x32_bf16 v[12:15], v[106:109], v[74:77], v[12:15]
	v_mfma_f32_16x16x32_bf16 v[8:11], v[200:203], v[74:77], v[8:11]
	v_mfma_f32_16x16x32_bf16 v[4:7], v[106:109], v[232:235], v[4:7]
	v_mfma_f32_16x16x32_bf16 v[0:3], v[200:203], v[232:235], v[0:3]
	global_load_dwordx4 v[74:77], v[30:31], off offset:1728
	global_load_dwordx4 v[106:109], v[26:27], off offset:1728
	global_load_dwordx4 v[200:203], v[28:29], off offset:1728
	global_load_dwordx4 v[232:235], v[24:25], off offset:1728
	s_waitcnt vmcnt(28)
	v_mfma_f32_16x16x32_bf16 v[12:15], v[110:113], v[78:81], v[12:15]
	v_mfma_f32_16x16x32_bf16 v[8:11], v[204:207], v[78:81], v[8:11]
	v_mfma_f32_16x16x32_bf16 v[4:7], v[110:113], v[162:165], v[4:7]
	v_mfma_f32_16x16x32_bf16 v[0:3], v[204:207], v[162:165], v[0:3]
	global_load_dwordx4 v[78:81], v[30:31], off offset:1792
	global_load_dwordx4 v[110:113], v[26:27], off offset:1792
	global_load_dwordx4 v[204:207], v[28:29], off offset:1792
	global_load_dwordx4 v[162:165], v[24:25], off offset:1792
	s_waitcnt vmcnt(28)
	v_mfma_f32_16x16x32_bf16 v[12:15], v[114:117], v[82:85], v[12:15]
	v_mfma_f32_16x16x32_bf16 v[8:11], v[208:211], v[82:85], v[8:11]
	v_mfma_f32_16x16x32_bf16 v[4:7], v[114:117], v[166:169], v[4:7]
	v_mfma_f32_16x16x32_bf16 v[0:3], v[208:211], v[166:169], v[0:3]
	global_load_dwordx4 v[82:85], v[30:31], off offset:1856
	global_load_dwordx4 v[114:117], v[26:27], off offset:1856
	global_load_dwordx4 v[208:211], v[28:29], off offset:1856
	global_load_dwordx4 v[166:169], v[24:25], off offset:1856
	s_waitcnt vmcnt(28)
	v_mfma_f32_16x16x32_bf16 v[12:15], v[118:121], v[86:89], v[12:15]
	v_mfma_f32_16x16x32_bf16 v[8:11], v[212:215], v[86:89], v[8:11]
	v_mfma_f32_16x16x32_bf16 v[4:7], v[118:121], v[170:173], v[4:7]
	v_mfma_f32_16x16x32_bf16 v[0:3], v[212:215], v[170:173], v[0:3]
	global_load_dwordx4 v[86:89], v[30:31], off offset:1920
	global_load_dwordx4 v[118:121], v[26:27], off offset:1920
	global_load_dwordx4 v[212:215], v[28:29], off offset:1920
	global_load_dwordx4 v[170:173], v[24:25], off offset:1920
	s_waitcnt vmcnt(28)
	v_mfma_f32_16x16x32_bf16 v[12:15], v[122:125], v[90:93], v[12:15]
	v_mfma_f32_16x16x32_bf16 v[8:11], v[216:219], v[90:93], v[8:11]
	v_mfma_f32_16x16x32_bf16 v[4:7], v[122:125], v[236:239], v[4:7]
	v_mfma_f32_16x16x32_bf16 v[0:3], v[216:219], v[236:239], v[0:3]
	global_load_dwordx4 v[90:93], v[30:31], off offset:1984
	global_load_dwordx4 v[122:125], v[26:27], off offset:1984
	global_load_dwordx4 v[216:219], v[28:29], off offset:1984
	global_load_dwordx4 v[236:239], v[24:25], off offset:1984
	s_waitcnt vmcnt(28)
	v_mfma_f32_16x16x32_bf16 v[12:15], v[94:97], v[62:65], v[12:15]
	v_mfma_f32_16x16x32_bf16 v[8:11], v[188:191], v[62:65], v[8:11]
	v_mfma_f32_16x16x32_bf16 v[4:7], v[94:97], v[220:223], v[4:7]
	v_mfma_f32_16x16x32_bf16 v[0:3], v[188:191], v[220:223], v[0:3]
	s_waitcnt vmcnt(24)
	v_mfma_f32_16x16x32_bf16 v[12:15], v[98:101], v[66:69], v[12:15]
	v_mfma_f32_16x16x32_bf16 v[8:11], v[192:195], v[66:69], v[8:11]
	v_mfma_f32_16x16x32_bf16 v[4:7], v[98:101], v[224:227], v[4:7]
	v_mfma_f32_16x16x32_bf16 v[0:3], v[192:195], v[224:227], v[0:3]
	s_waitcnt vmcnt(20)
	v_mfma_f32_16x16x32_bf16 v[12:15], v[102:105], v[70:73], v[12:15]
	v_mfma_f32_16x16x32_bf16 v[8:11], v[196:199], v[70:73], v[8:11]
	v_mfma_f32_16x16x32_bf16 v[4:7], v[102:105], v[228:231], v[4:7]
	v_mfma_f32_16x16x32_bf16 v[0:3], v[196:199], v[228:231], v[0:3]
	s_waitcnt vmcnt(16)
	v_mfma_f32_16x16x32_bf16 v[12:15], v[106:109], v[74:77], v[12:15]
	v_mfma_f32_16x16x32_bf16 v[8:11], v[200:203], v[74:77], v[8:11]
	v_mfma_f32_16x16x32_bf16 v[4:7], v[106:109], v[232:235], v[4:7]
	v_mfma_f32_16x16x32_bf16 v[0:3], v[200:203], v[232:235], v[0:3]
	s_waitcnt vmcnt(12)
	v_mfma_f32_16x16x32_bf16 v[12:15], v[110:113], v[78:81], v[12:15]
	v_mfma_f32_16x16x32_bf16 v[8:11], v[204:207], v[78:81], v[8:11]
	v_mfma_f32_16x16x32_bf16 v[4:7], v[110:113], v[162:165], v[4:7]
	v_mfma_f32_16x16x32_bf16 v[0:3], v[204:207], v[162:165], v[0:3]
	s_waitcnt vmcnt(8)
	v_mfma_f32_16x16x32_bf16 v[12:15], v[114:117], v[82:85], v[12:15]
	v_mfma_f32_16x16x32_bf16 v[8:11], v[208:211], v[82:85], v[8:11]
	v_mfma_f32_16x16x32_bf16 v[4:7], v[114:117], v[166:169], v[4:7]
	v_mfma_f32_16x16x32_bf16 v[0:3], v[208:211], v[166:169], v[0:3]
	s_waitcnt vmcnt(4)
	v_mfma_f32_16x16x32_bf16 v[12:15], v[118:121], v[86:89], v[12:15]
	v_mfma_f32_16x16x32_bf16 v[8:11], v[212:215], v[86:89], v[8:11]
	v_mfma_f32_16x16x32_bf16 v[4:7], v[118:121], v[170:173], v[4:7]
	v_mfma_f32_16x16x32_bf16 v[0:3], v[212:215], v[170:173], v[0:3]
	s_waitcnt vmcnt(0)
	v_mfma_f32_16x16x32_bf16 v[12:15], v[122:125], v[90:93], v[12:15]
	v_mfma_f32_16x16x32_bf16 v[8:11], v[216:219], v[90:93], v[8:11]
	v_mfma_f32_16x16x32_bf16 v[4:7], v[122:125], v[236:239], v[4:7]
	v_mfma_f32_16x16x32_bf16 v[0:3], v[216:219], v[236:239], v[0:3]
	s_nop 1
	s_lshl_b32 s10, s8, 7
	s_and_b32 s10, s10, 0xf80
	v_or_b32_e32 v22, s10, v32
	s_mov_b32 s10, 0xc0135761
	v_pk_mul_f32 v[24:25], v[14:15], v[14:15]
	v_pk_mul_f32 v[26:27], v[12:13], v[12:13]
	v_mov_b64_e32 v[28:29], s[10:11]
	s_mov_b32 s10, 0x3dd2d3e7
	v_pk_fma_f32 v[26:27], v[26:27], s[10:11], v[28:29] op_sel_hi:[1,0,0] neg_lo:[1,0,0] neg_hi:[1,0,0]
	v_pk_fma_f32 v[24:25], v[24:25], s[10:11], v[28:29] op_sel_hi:[1,0,0] neg_lo:[1,0,0] neg_hi:[1,0,0]
	v_pk_mul_f32 v[26:27], v[12:13], v[26:27]
	v_pk_mul_f32 v[24:25], v[14:15], v[24:25]
	v_exp_f32_e32 v26, v26
	v_exp_f32_e32 v27, v27
	v_exp_f32_e32 v24, v24
	v_exp_f32_e32 v25, v25
	s_lshl_b32 s9, s8, 1
	v_pk_add_f32 v[26:27], v[26:27], 1.0 op_sel_hi:[1,0]
	s_andn2_b32 s9, s9, 63
	v_pk_add_f32 v[24:25], v[24:25], 1.0 op_sel_hi:[1,0]
	v_rcp_f32_e32 v26, v26
	v_rcp_f32_e32 v27, v27
	v_rcp_f32_e32 v24, v24
	v_rcp_f32_e32 v25, v25
	v_add_u32_e32 v20, s9, v33
	v_pk_mul_f32 v[12:13], v[12:13], v[26:27]
	v_pk_mul_f32 v[26:27], v[8:9], v[8:9]
	v_pk_mul_f32 v[14:15], v[14:15], v[24:25]
	v_pk_mul_f32 v[24:25], v[10:11], v[10:11]
	v_pk_fma_f32 v[26:27], v[26:27], s[10:11], v[28:29] op_sel_hi:[1,0,0] neg_lo:[1,0,0] neg_hi:[1,0,0]
	v_pk_fma_f32 v[24:25], v[24:25], s[10:11], v[28:29] op_sel_hi:[1,0,0] neg_lo:[1,0,0] neg_hi:[1,0,0]
	v_pk_mul_f32 v[26:27], v[8:9], v[26:27]
	v_pk_mul_f32 v[24:25], v[10:11], v[24:25]
	v_exp_f32_e32 v26, v26
	v_exp_f32_e32 v27, v27
	v_exp_f32_e32 v24, v24
	v_exp_f32_e32 v25, v25
	v_ashrrev_i32_e32 v21, 31, v20
	v_pk_add_f32 v[26:27], v[26:27], 1.0 op_sel_hi:[1,0]
	v_lshlrev_b32_e32 v148, 1, v22
	v_pk_add_f32 v[24:25], v[24:25], 1.0 op_sel_hi:[1,0]
	v_rcp_f32_e32 v26, v26
	v_rcp_f32_e32 v27, v27
	v_rcp_f32_e32 v24, v24
	v_rcp_f32_e32 v25, v25
	v_lshl_add_u64 v[22:23], v[16:17], 0, v[148:149]
	v_lshlrev_b64 v[30:31], 13, v[20:21]
	v_lshl_add_u64 v[30:31], v[22:23], 0, v[30:31]
	v_cvt_pk_bf16_f32 v12, v12, v13
	v_cvt_pk_bf16_f32 v13, v14, v15
	global_store_dwordx2 v[30:31], v[12:13], off
	v_pk_mul_f32 v[8:9], v[8:9], v[26:27]
	v_pk_mul_f32 v[10:11], v[10:11], v[24:25]
	v_pk_mul_f32 v[12:13], v[4:5], v[4:5]
	v_cvt_pk_bf16_f32 v8, v8, v9
	v_cvt_pk_bf16_f32 v9, v10, v11
	v_pk_mul_f32 v[10:11], v[6:7], v[6:7]
	v_pk_fma_f32 v[12:13], v[12:13], s[10:11], v[28:29] op_sel_hi:[1,0,0] neg_lo:[1,0,0] neg_hi:[1,0,0]
	v_pk_fma_f32 v[10:11], v[10:11], s[10:11], v[28:29] op_sel_hi:[1,0,0] neg_lo:[1,0,0] neg_hi:[1,0,0]
	v_pk_mul_f32 v[12:13], v[4:5], v[12:13]
	v_pk_mul_f32 v[10:11], v[6:7], v[10:11]
	v_exp_f32_e32 v12, v12
	v_exp_f32_e32 v13, v13
	v_exp_f32_e32 v10, v10
	v_exp_f32_e32 v11, v11
	global_store_dwordx2 v[30:31], v[8:9], off offset:32
	v_pk_add_f32 v[12:13], v[12:13], 1.0 op_sel_hi:[1,0]
	v_or_b32_e32 v8, 16, v20
	v_rcp_f32_e32 v12, v12
	v_rcp_f32_e32 v13, v13
	v_pk_add_f32 v[10:11], v[10:11], 1.0 op_sel_hi:[1,0]
	v_ashrrev_i32_e32 v9, 31, v8
	v_rcp_f32_e32 v10, v10
	v_rcp_f32_e32 v11, v11
	v_pk_mul_f32 v[4:5], v[4:5], v[12:13]
	v_pk_mul_f32 v[12:13], v[0:1], v[0:1]
	v_lshlrev_b64 v[8:9], 13, v[8:9]
	v_pk_mul_f32 v[6:7], v[6:7], v[10:11]
	v_pk_mul_f32 v[10:11], v[2:3], v[2:3]
	v_pk_fma_f32 v[12:13], v[12:13], s[10:11], v[28:29] op_sel_hi:[1,0,0] neg_lo:[1,0,0] neg_hi:[1,0,0]
	v_pk_fma_f32 v[10:11], v[10:11], s[10:11], v[28:29] op_sel_hi:[1,0,0] neg_lo:[1,0,0] neg_hi:[1,0,0]
	v_pk_mul_f32 v[12:13], v[0:1], v[12:13]
	v_pk_mul_f32 v[10:11], v[2:3], v[10:11]
	v_exp_f32_e32 v12, v12
	v_exp_f32_e32 v13, v13
	v_exp_f32_e32 v10, v10
	v_exp_f32_e32 v11, v11
	s_add_i32 s8, s8, s86
	v_pk_add_f32 v[12:13], v[12:13], 1.0 op_sel_hi:[1,0]
	s_add_i32 s5, s5, s11
	v_rcp_f32_e32 v12, v12
	v_rcp_f32_e32 v13, v13
	v_pk_add_f32 v[10:11], v[10:11], 1.0 op_sel_hi:[1,0]
	s_add_i32 s4, s4, s14
	v_rcp_f32_e32 v10, v10
	v_rcp_f32_e32 v11, v11
	v_lshl_add_u64 v[8:9], v[22:23], 0, v[8:9]
	v_pk_mul_f32 v[0:1], v[0:1], v[12:13]
	s_cmpk_gt_i32 s8, 0xff
	v_cvt_pk_bf16_f32 v4, v4, v5
	v_cvt_pk_bf16_f32 v5, v6, v7
	global_store_dwordx2 v[8:9], v[4:5], off
	v_pk_mul_f32 v[2:3], v[2:3], v[10:11]
	v_cvt_pk_bf16_f32 v0, v0, v1
	s_nop 0
	v_cvt_pk_bf16_f32 v1, v2, v3
	global_store_dwordx2 v[8:9], v[0:1], off offset:32
	s_cbranch_scc0 .LBB0_309

.LBB0_712:
	s_and_b32 s3, s1, 0xffffffc0
	v_add_u32_e32 v0, s3, v59
	s_lshl_b32 s3, s0, 11
	s_and_b32 s3, s3, 0x7c0000
	v_readlane_b32 s24, v245, 13
	v_lshl_or_b32 v148, v60, 11, s3
	v_readlane_b32 s25, v245, 14
	v_ashrrev_i32_e32 v1, 31, v0
	v_lshlrev_b64 v[0:1], 11, v[0:1]
	v_lshl_add_u64 v[30:31], s[24:25], 0, v[148:149]
	v_readlane_b32 s24, v245, 15
	v_readlane_b32 s25, v245, 16
	v_lshl_add_u64 v[20:21], s[88:89], 0, v[0:1]
	v_mov_b32_e32 v0, 0
	v_lshl_add_u64 v[32:33], s[24:25], 0, v[148:149]
	v_readlane_b32 s24, v245, 17
	v_readlane_b32 s25, v245, 18
	v_lshl_add_u64 v[22:23], s[10:11], 0, v[148:149]
	v_lshl_add_u64 v[24:25], s[14:15], 0, v[148:149]
	v_lshl_add_u64 v[34:35], s[24:25], 0, v[148:149]
	v_readlane_b32 s24, v245, 19
	v_readlane_b32 s25, v245, 20
	v_lshl_add_u64 v[26:27], s[20:21], 0, v[148:149]
	v_lshl_add_u64 v[28:29], s[22:23], 0, v[148:149]
	v_lshl_add_u64 v[36:37], s[24:25], 0, v[148:149]
	v_readlane_b32 s24, v245, 21
	v_readlane_b32 s25, v245, 22
	s_movk_i32 s3, 0xffe0
	v_mov_b32_e32 v1, v0
	v_lshl_add_u64 v[38:39], s[24:25], 0, v[148:149]
	v_readlane_b32 s24, v245, 23
	v_readlane_b32 s25, v245, 24
	v_mov_b32_e32 v2, v0
	v_mov_b32_e32 v3, v0
	v_lshl_add_u64 v[40:41], s[24:25], 0, v[148:149]
	v_readlane_b32 s24, v245, 25
	v_readlane_b32 s25, v245, 26
	v_mov_b32_e32 v4, v0
	v_mov_b32_e32 v5, v0
	v_lshl_add_u64 v[42:43], s[24:25], 0, v[148:149]
	v_readlane_b32 s24, v245, 27
	v_readlane_b32 s25, v245, 28
	v_mov_b32_e32 v6, v0
	v_mov_b32_e32 v7, v0
	v_lshl_add_u64 v[44:45], s[24:25], 0, v[148:149]
	v_readlane_b32 s24, v245, 29
	v_readlane_b32 s25, v245, 30
	v_mov_b32_e32 v8, v0
	v_mov_b32_e32 v9, v0
	v_lshl_add_u64 v[46:47], s[24:25], 0, v[148:149]
	v_readlane_b32 s24, v245, 31
	v_readlane_b32 s25, v245, 32
	v_mov_b32_e32 v10, v0
	v_mov_b32_e32 v11, v0
	v_lshl_add_u64 v[48:49], s[24:25], 0, v[148:149]
	v_readlane_b32 s24, v245, 40
	v_readlane_b32 s25, v245, 41
	v_mov_b32_e32 v12, v0
	v_mov_b32_e32 v13, v0
	v_lshl_add_u64 v[50:51], s[24:25], 0, v[148:149]
	v_readlane_b32 s24, v245, 33
	v_readlane_b32 s25, v245, 34
	v_mov_b32_e32 v14, v0
	v_mov_b32_e32 v15, v0
	v_lshl_add_u64 v[52:53], s[24:25], 0, v[148:149]
	v_lshl_add_u64 v[56:57], v[20:21], 0, v[18:19]
	v_add_co_u32_e32 v54, vcc, s7, v56
	s_nop 1
	v_addc_co_u32_e32 v55, vcc, 0, v57, vcc
	v_add_co_u32_e32 v56, vcc, s30, v56
	s_nop 1
	v_addc_co_u32_e32 v57, vcc, 0, v57, vcc
	v_lshl_add_u64 v[50:51], v[50:51], 0, v[18:19]
	v_lshl_add_u64 v[52:53], v[52:53], 0, v[18:19]
	global_load_dwordx4 v[62:65], v[54:55], off
	global_load_dwordx4 v[94:97], v[50:51], off
	global_load_dwordx4 v[188:191], v[52:53], off
	global_load_dwordx4 v[220:223], v[56:57], off
	global_load_dwordx4 v[66:69], v[54:55], off offset:64
	global_load_dwordx4 v[98:101], v[50:51], off offset:64
	global_load_dwordx4 v[192:195], v[52:53], off offset:64
	global_load_dwordx4 v[224:227], v[56:57], off offset:64
	global_load_dwordx4 v[70:73], v[54:55], off offset:128
	global_load_dwordx4 v[102:105], v[50:51], off offset:128
	global_load_dwordx4 v[196:199], v[52:53], off offset:128
	global_load_dwordx4 v[228:231], v[56:57], off offset:128
	global_load_dwordx4 v[74:77], v[54:55], off offset:192
	global_load_dwordx4 v[106:109], v[50:51], off offset:192
	global_load_dwordx4 v[200:203], v[52:53], off offset:192
	global_load_dwordx4 v[232:235], v[56:57], off offset:192
	global_load_dwordx4 v[78:81], v[54:55], off offset:256
	global_load_dwordx4 v[110:113], v[50:51], off offset:256
	global_load_dwordx4 v[204:207], v[52:53], off offset:256
	global_load_dwordx4 v[162:165], v[56:57], off offset:256
	global_load_dwordx4 v[82:85], v[54:55], off offset:320
	global_load_dwordx4 v[114:117], v[50:51], off offset:320
	global_load_dwordx4 v[208:211], v[52:53], off offset:320
	global_load_dwordx4 v[166:169], v[56:57], off offset:320
	global_load_dwordx4 v[86:89], v[54:55], off offset:384
	global_load_dwordx4 v[118:121], v[50:51], off offset:384
	global_load_dwordx4 v[212:215], v[52:53], off offset:384
	global_load_dwordx4 v[170:173], v[56:57], off offset:384
	global_load_dwordx4 v[90:93], v[54:55], off offset:448
	global_load_dwordx4 v[122:125], v[50:51], off offset:448
	global_load_dwordx4 v[216:219], v[52:53], off offset:448
	global_load_dwordx4 v[236:239], v[56:57], off offset:448
	s_waitcnt vmcnt(28)
	v_mfma_f32_16x16x32_bf16 v[12:15], v[94:97], v[62:65], v[12:15]
	v_mfma_f32_16x16x32_bf16 v[8:11], v[188:191], v[62:65], v[8:11]
	v_mfma_f32_16x16x32_bf16 v[4:7], v[94:97], v[220:223], v[4:7]
	v_mfma_f32_16x16x32_bf16 v[0:3], v[188:191], v[220:223], v[0:3]
	global_load_dwordx4 v[62:65], v[54:55], off offset:512
	global_load_dwordx4 v[94:97], v[50:51], off offset:512
	global_load_dwordx4 v[188:191], v[52:53], off offset:512
	global_load_dwordx4 v[220:223], v[56:57], off offset:512
	s_waitcnt vmcnt(28)
	v_mfma_f32_16x16x32_bf16 v[12:15], v[98:101], v[66:69], v[12:15]
	v_mfma_f32_16x16x32_bf16 v[8:11], v[192:195], v[66:69], v[8:11]
	v_mfma_f32_16x16x32_bf16 v[4:7], v[98:101], v[224:227], v[4:7]
	v_mfma_f32_16x16x32_bf16 v[0:3], v[192:195], v[224:227], v[0:3]
	global_load_dwordx4 v[66:69], v[54:55], off offset:576
	global_load_dwordx4 v[98:101], v[50:51], off offset:576
	global_load_dwordx4 v[192:195], v[52:53], off offset:576
	global_load_dwordx4 v[224:227], v[56:57], off offset:576
	s_waitcnt vmcnt(28)
	v_mfma_f32_16x16x32_bf16 v[12:15], v[102:105], v[70:73], v[12:15]
	v_mfma_f32_16x16x32_bf16 v[8:11], v[196:199], v[70:73], v[8:11]
	v_mfma_f32_16x16x32_bf16 v[4:7], v[102:105], v[228:231], v[4:7]
	v_mfma_f32_16x16x32_bf16 v[0:3], v[196:199], v[228:231], v[0:3]
	global_load_dwordx4 v[70:73], v[54:55], off offset:640
	global_load_dwordx4 v[102:105], v[50:51], off offset:640
	global_load_dwordx4 v[196:199], v[52:53], off offset:640
	global_load_dwordx4 v[228:231], v[56:57], off offset:640
	s_waitcnt vmcnt(28)
	v_mfma_f32_16x16x32_bf16 v[12:15], v[106:109], v[74:77], v[12:15]
	v_mfma_f32_16x16x32_bf16 v[8:11], v[200:203], v[74:77], v[8:11]
	v_mfma_f32_16x16x32_bf16 v[4:7], v[106:109], v[232:235], v[4:7]
	v_mfma_f32_16x16x32_bf16 v[0:3], v[200:203], v[232:235], v[0:3]
	global_load_dwordx4 v[74:77], v[54:55], off offset:704
	global_load_dwordx4 v[106:109], v[50:51], off offset:704
	global_load_dwordx4 v[200:203], v[52:53], off offset:704
	global_load_dwordx4 v[232:235], v[56:57], off offset:704
	s_waitcnt vmcnt(28)
	v_mfma_f32_16x16x32_bf16 v[12:15], v[110:113], v[78:81], v[12:15]
	v_mfma_f32_16x16x32_bf16 v[8:11], v[204:207], v[78:81], v[8:11]
	v_mfma_f32_16x16x32_bf16 v[4:7], v[110:113], v[162:165], v[4:7]
	v_mfma_f32_16x16x32_bf16 v[0:3], v[204:207], v[162:165], v[0:3]
	global_load_dwordx4 v[78:81], v[54:55], off offset:768
	global_load_dwordx4 v[110:113], v[50:51], off offset:768
	global_load_dwordx4 v[204:207], v[52:53], off offset:768
	global_load_dwordx4 v[162:165], v[56:57], off offset:768
	s_waitcnt vmcnt(28)
	v_mfma_f32_16x16x32_bf16 v[12:15], v[114:117], v[82:85], v[12:15]
	v_mfma_f32_16x16x32_bf16 v[8:11], v[208:211], v[82:85], v[8:11]
	v_mfma_f32_16x16x32_bf16 v[4:7], v[114:117], v[166:169], v[4:7]
	v_mfma_f32_16x16x32_bf16 v[0:3], v[208:211], v[166:169], v[0:3]
	global_load_dwordx4 v[82:85], v[54:55], off offset:832
	global_load_dwordx4 v[114:117], v[50:51], off offset:832
	global_load_dwordx4 v[208:211], v[52:53], off offset:832
	global_load_dwordx4 v[166:169], v[56:57], off offset:832
	s_waitcnt vmcnt(28)
	v_mfma_f32_16x16x32_bf16 v[12:15], v[118:121], v[86:89], v[12:15]
	v_mfma_f32_16x16x32_bf16 v[8:11], v[212:215], v[86:89], v[8:11]
	v_mfma_f32_16x16x32_bf16 v[4:7], v[118:121], v[170:173], v[4:7]
	v_mfma_f32_16x16x32_bf16 v[0:3], v[212:215], v[170:173], v[0:3]
	global_load_dwordx4 v[86:89], v[54:55], off offset:896
	global_load_dwordx4 v[118:121], v[50:51], off offset:896
	global_load_dwordx4 v[212:215], v[52:53], off offset:896
	global_load_dwordx4 v[170:173], v[56:57], off offset:896
	s_waitcnt vmcnt(28)
	v_mfma_f32_16x16x32_bf16 v[12:15], v[122:125], v[90:93], v[12:15]
	v_mfma_f32_16x16x32_bf16 v[8:11], v[216:219], v[90:93], v[8:11]
	v_mfma_f32_16x16x32_bf16 v[4:7], v[122:125], v[236:239], v[4:7]
	v_mfma_f32_16x16x32_bf16 v[0:3], v[216:219], v[236:239], v[0:3]
	global_load_dwordx4 v[90:93], v[54:55], off offset:960
	global_load_dwordx4 v[122:125], v[50:51], off offset:960
	global_load_dwordx4 v[216:219], v[52:53], off offset:960
	global_load_dwordx4 v[236:239], v[56:57], off offset:960
	s_waitcnt vmcnt(28)
	v_mfma_f32_16x16x32_bf16 v[12:15], v[94:97], v[62:65], v[12:15]
	v_mfma_f32_16x16x32_bf16 v[8:11], v[188:191], v[62:65], v[8:11]
	v_mfma_f32_16x16x32_bf16 v[4:7], v[94:97], v[220:223], v[4:7]
	v_mfma_f32_16x16x32_bf16 v[0:3], v[188:191], v[220:223], v[0:3]
	global_load_dwordx4 v[62:65], v[54:55], off offset:1024
	global_load_dwordx4 v[94:97], v[50:51], off offset:1024
	global_load_dwordx4 v[188:191], v[52:53], off offset:1024
	global_load_dwordx4 v[220:223], v[56:57], off offset:1024
	s_waitcnt vmcnt(28)
	v_mfma_f32_16x16x32_bf16 v[12:15], v[98:101], v[66:69], v[12:15]
	v_mfma_f32_16x16x32_bf16 v[8:11], v[192:195], v[66:69], v[8:11]
	v_mfma_f32_16x16x32_bf16 v[4:7], v[98:101], v[224:227], v[4:7]
	v_mfma_f32_16x16x32_bf16 v[0:3], v[192:195], v[224:227], v[0:3]
	global_load_dwordx4 v[66:69], v[54:55], off offset:1088
	global_load_dwordx4 v[98:101], v[50:51], off offset:1088
	global_load_dwordx4 v[192:195], v[52:53], off offset:1088
	global_load_dwordx4 v[224:227], v[56:57], off offset:1088
	s_waitcnt vmcnt(28)
	v_mfma_f32_16x16x32_bf16 v[12:15], v[102:105], v[70:73], v[12:15]
	v_mfma_f32_16x16x32_bf16 v[8:11], v[196:199], v[70:73], v[8:11]
	v_mfma_f32_16x16x32_bf16 v[4:7], v[102:105], v[228:231], v[4:7]
	v_mfma_f32_16x16x32_bf16 v[0:3], v[196:199], v[228:231], v[0:3]
	global_load_dwordx4 v[70:73], v[54:55], off offset:1152
	global_load_dwordx4 v[102:105], v[50:51], off offset:1152
	global_load_dwordx4 v[196:199], v[52:53], off offset:1152
	global_load_dwordx4 v[228:231], v[56:57], off offset:1152
	s_waitcnt vmcnt(28)
	v_mfma_f32_16x16x32_bf16 v[12:15], v[106:109], v[74:77], v[12:15]
	v_mfma_f32_16x16x32_bf16 v[8:11], v[200:203], v[74:77], v[8:11]
	v_mfma_f32_16x16x32_bf16 v[4:7], v[106:109], v[232:235], v[4:7]
	v_mfma_f32_16x16x32_bf16 v[0:3], v[200:203], v[232:235], v[0:3]
	global_load_dwordx4 v[74:77], v[54:55], off offset:1216
	global_load_dwordx4 v[106:109], v[50:51], off offset:1216
	global_load_dwordx4 v[200:203], v[52:53], off offset:1216
	global_load_dwordx4 v[232:235], v[56:57], off offset:1216
	s_waitcnt vmcnt(28)
	v_mfma_f32_16x16x32_bf16 v[12:15], v[110:113], v[78:81], v[12:15]
	v_mfma_f32_16x16x32_bf16 v[8:11], v[204:207], v[78:81], v[8:11]
	v_mfma_f32_16x16x32_bf16 v[4:7], v[110:113], v[162:165], v[4:7]
	v_mfma_f32_16x16x32_bf16 v[0:3], v[204:207], v[162:165], v[0:3]
	global_load_dwordx4 v[78:81], v[54:55], off offset:1280
	global_load_dwordx4 v[110:113], v[50:51], off offset:1280
	global_load_dwordx4 v[204:207], v[52:53], off offset:1280
	global_load_dwordx4 v[162:165], v[56:57], off offset:1280
	s_waitcnt vmcnt(28)
	v_mfma_f32_16x16x32_bf16 v[12:15], v[114:117], v[82:85], v[12:15]
	v_mfma_f32_16x16x32_bf16 v[8:11], v[208:211], v[82:85], v[8:11]
	v_mfma_f32_16x16x32_bf16 v[4:7], v[114:117], v[166:169], v[4:7]
	v_mfma_f32_16x16x32_bf16 v[0:3], v[208:211], v[166:169], v[0:3]
	global_load_dwordx4 v[82:85], v[54:55], off offset:1344
	global_load_dwordx4 v[114:117], v[50:51], off offset:1344
	global_load_dwordx4 v[208:211], v[52:53], off offset:1344
	global_load_dwordx4 v[166:169], v[56:57], off offset:1344
	s_waitcnt vmcnt(28)
	v_mfma_f32_16x16x32_bf16 v[12:15], v[118:121], v[86:89], v[12:15]
	v_mfma_f32_16x16x32_bf16 v[8:11], v[212:215], v[86:89], v[8:11]
	v_mfma_f32_16x16x32_bf16 v[4:7], v[118:121], v[170:173], v[4:7]
	v_mfma_f32_16x16x32_bf16 v[0:3], v[212:215], v[170:173], v[0:3]
	global_load_dwordx4 v[86:89], v[54:55], off offset:1408
	global_load_dwordx4 v[118:121], v[50:51], off offset:1408
	global_load_dwordx4 v[212:215], v[52:53], off offset:1408
	global_load_dwordx4 v[170:173], v[56:57], off offset:1408
	s_waitcnt vmcnt(28)
	v_mfma_f32_16x16x32_bf16 v[12:15], v[122:125], v[90:93], v[12:15]
	v_mfma_f32_16x16x32_bf16 v[8:11], v[216:219], v[90:93], v[8:11]
	v_mfma_f32_16x16x32_bf16 v[4:7], v[122:125], v[236:239], v[4:7]
	v_mfma_f32_16x16x32_bf16 v[0:3], v[216:219], v[236:239], v[0:3]
	global_load_dwordx4 v[90:93], v[54:55], off offset:1472
	global_load_dwordx4 v[122:125], v[50:51], off offset:1472
	global_load_dwordx4 v[216:219], v[52:53], off offset:1472
	global_load_dwordx4 v[236:239], v[56:57], off offset:1472
	s_waitcnt vmcnt(28)
	v_mfma_f32_16x16x32_bf16 v[12:15], v[94:97], v[62:65], v[12:15]
	v_mfma_f32_16x16x32_bf16 v[8:11], v[188:191], v[62:65], v[8:11]
	v_mfma_f32_16x16x32_bf16 v[4:7], v[94:97], v[220:223], v[4:7]
	v_mfma_f32_16x16x32_bf16 v[0:3], v[188:191], v[220:223], v[0:3]
	global_load_dwordx4 v[62:65], v[54:55], off offset:1536
	global_load_dwordx4 v[94:97], v[50:51], off offset:1536
	global_load_dwordx4 v[188:191], v[52:53], off offset:1536
	global_load_dwordx4 v[220:223], v[56:57], off offset:1536
	s_waitcnt vmcnt(28)
	v_mfma_f32_16x16x32_bf16 v[12:15], v[98:101], v[66:69], v[12:15]
	v_mfma_f32_16x16x32_bf16 v[8:11], v[192:195], v[66:69], v[8:11]
	v_mfma_f32_16x16x32_bf16 v[4:7], v[98:101], v[224:227], v[4:7]
	v_mfma_f32_16x16x32_bf16 v[0:3], v[192:195], v[224:227], v[0:3]
	global_load_dwordx4 v[66:69], v[54:55], off offset:1600
	global_load_dwordx4 v[98:101], v[50:51], off offset:1600
	global_load_dwordx4 v[192:195], v[52:53], off offset:1600
	global_load_dwordx4 v[224:227], v[56:57], off offset:1600
	s_waitcnt vmcnt(28)
	v_mfma_f32_16x16x32_bf16 v[12:15], v[102:105], v[70:73], v[12:15]
	v_mfma_f32_16x16x32_bf16 v[8:11], v[196:199], v[70:73], v[8:11]
	v_mfma_f32_16x16x32_bf16 v[4:7], v[102:105], v[228:231], v[4:7]
	v_mfma_f32_16x16x32_bf16 v[0:3], v[196:199], v[228:231], v[0:3]
	global_load_dwordx4 v[70:73], v[54:55], off offset:1664
	global_load_dwordx4 v[102:105], v[50:51], off offset:1664
	global_load_dwordx4 v[196:199], v[52:53], off offset:1664
	global_load_dwordx4 v[228:231], v[56:57], off offset:1664
	s_waitcnt vmcnt(28)
	v_mfma_f32_16x16x32_bf16 v[12:15], v[106:109], v[74:77], v[12:15]
	v_mfma_f32_16x16x32_bf16 v[8:11], v[200:203], v[74:77], v[8:11]
	v_mfma_f32_16x16x32_bf16 v[4:7], v[106:109], v[232:235], v[4:7]
	v_mfma_f32_16x16x32_bf16 v[0:3], v[200:203], v[232:235], v[0:3]
	global_load_dwordx4 v[74:77], v[54:55], off offset:1728
	global_load_dwordx4 v[106:109], v[50:51], off offset:1728
	global_load_dwordx4 v[200:203], v[52:53], off offset:1728
	global_load_dwordx4 v[232:235], v[56:57], off offset:1728
	s_waitcnt vmcnt(28)
	v_mfma_f32_16x16x32_bf16 v[12:15], v[110:113], v[78:81], v[12:15]
	v_mfma_f32_16x16x32_bf16 v[8:11], v[204:207], v[78:81], v[8:11]
	v_mfma_f32_16x16x32_bf16 v[4:7], v[110:113], v[162:165], v[4:7]
	v_mfma_f32_16x16x32_bf16 v[0:3], v[204:207], v[162:165], v[0:3]
	global_load_dwordx4 v[78:81], v[54:55], off offset:1792
	global_load_dwordx4 v[110:113], v[50:51], off offset:1792
	global_load_dwordx4 v[204:207], v[52:53], off offset:1792
	global_load_dwordx4 v[162:165], v[56:57], off offset:1792
	s_waitcnt vmcnt(28)
	v_mfma_f32_16x16x32_bf16 v[12:15], v[114:117], v[82:85], v[12:15]
	v_mfma_f32_16x16x32_bf16 v[8:11], v[208:211], v[82:85], v[8:11]
	v_mfma_f32_16x16x32_bf16 v[4:7], v[114:117], v[166:169], v[4:7]
	v_mfma_f32_16x16x32_bf16 v[0:3], v[208:211], v[166:169], v[0:3]
	global_load_dwordx4 v[82:85], v[54:55], off offset:1856
	global_load_dwordx4 v[114:117], v[50:51], off offset:1856
	global_load_dwordx4 v[208:211], v[52:53], off offset:1856
	global_load_dwordx4 v[166:169], v[56:57], off offset:1856
	s_waitcnt vmcnt(28)
	v_mfma_f32_16x16x32_bf16 v[12:15], v[118:121], v[86:89], v[12:15]
	v_mfma_f32_16x16x32_bf16 v[8:11], v[212:215], v[86:89], v[8:11]
	v_mfma_f32_16x16x32_bf16 v[4:7], v[118:121], v[170:173], v[4:7]
	v_mfma_f32_16x16x32_bf16 v[0:3], v[212:215], v[170:173], v[0:3]
	global_load_dwordx4 v[86:89], v[54:55], off offset:1920
	global_load_dwordx4 v[118:121], v[50:51], off offset:1920
	global_load_dwordx4 v[212:215], v[52:53], off offset:1920
	global_load_dwordx4 v[170:173], v[56:57], off offset:1920
	s_waitcnt vmcnt(28)
	v_mfma_f32_16x16x32_bf16 v[12:15], v[122:125], v[90:93], v[12:15]
	v_mfma_f32_16x16x32_bf16 v[8:11], v[216:219], v[90:93], v[8:11]
	v_mfma_f32_16x16x32_bf16 v[4:7], v[122:125], v[236:239], v[4:7]
	v_mfma_f32_16x16x32_bf16 v[0:3], v[216:219], v[236:239], v[0:3]
	global_load_dwordx4 v[90:93], v[54:55], off offset:1984
	global_load_dwordx4 v[122:125], v[50:51], off offset:1984
	global_load_dwordx4 v[216:219], v[52:53], off offset:1984
	global_load_dwordx4 v[236:239], v[56:57], off offset:1984
	s_waitcnt vmcnt(28)
	v_mfma_f32_16x16x32_bf16 v[12:15], v[94:97], v[62:65], v[12:15]
	v_mfma_f32_16x16x32_bf16 v[8:11], v[188:191], v[62:65], v[8:11]
	v_mfma_f32_16x16x32_bf16 v[4:7], v[94:97], v[220:223], v[4:7]
	v_mfma_f32_16x16x32_bf16 v[0:3], v[188:191], v[220:223], v[0:3]
	s_waitcnt vmcnt(24)
	v_mfma_f32_16x16x32_bf16 v[12:15], v[98:101], v[66:69], v[12:15]
	v_mfma_f32_16x16x32_bf16 v[8:11], v[192:195], v[66:69], v[8:11]
	v_mfma_f32_16x16x32_bf16 v[4:7], v[98:101], v[224:227], v[4:7]
	v_mfma_f32_16x16x32_bf16 v[0:3], v[192:195], v[224:227], v[0:3]
	s_waitcnt vmcnt(20)
	v_mfma_f32_16x16x32_bf16 v[12:15], v[102:105], v[70:73], v[12:15]
	v_mfma_f32_16x16x32_bf16 v[8:11], v[196:199], v[70:73], v[8:11]
	v_mfma_f32_16x16x32_bf16 v[4:7], v[102:105], v[228:231], v[4:7]
	v_mfma_f32_16x16x32_bf16 v[0:3], v[196:199], v[228:231], v[0:3]
	s_waitcnt vmcnt(16)
	v_mfma_f32_16x16x32_bf16 v[12:15], v[106:109], v[74:77], v[12:15]
	v_mfma_f32_16x16x32_bf16 v[8:11], v[200:203], v[74:77], v[8:11]
	v_mfma_f32_16x16x32_bf16 v[4:7], v[106:109], v[232:235], v[4:7]
	v_mfma_f32_16x16x32_bf16 v[0:3], v[200:203], v[232:235], v[0:3]
	s_waitcnt vmcnt(12)
	v_mfma_f32_16x16x32_bf16 v[12:15], v[110:113], v[78:81], v[12:15]
	v_mfma_f32_16x16x32_bf16 v[8:11], v[204:207], v[78:81], v[8:11]
	v_mfma_f32_16x16x32_bf16 v[4:7], v[110:113], v[162:165], v[4:7]
	v_mfma_f32_16x16x32_bf16 v[0:3], v[204:207], v[162:165], v[0:3]
	s_waitcnt vmcnt(8)
	v_mfma_f32_16x16x32_bf16 v[12:15], v[114:117], v[82:85], v[12:15]
	v_mfma_f32_16x16x32_bf16 v[8:11], v[208:211], v[82:85], v[8:11]
	v_mfma_f32_16x16x32_bf16 v[4:7], v[114:117], v[166:169], v[4:7]
	v_mfma_f32_16x16x32_bf16 v[0:3], v[208:211], v[166:169], v[0:3]
	s_waitcnt vmcnt(4)
	v_mfma_f32_16x16x32_bf16 v[12:15], v[118:121], v[86:89], v[12:15]
	v_mfma_f32_16x16x32_bf16 v[8:11], v[212:215], v[86:89], v[8:11]
	v_mfma_f32_16x16x32_bf16 v[4:7], v[118:121], v[170:173], v[4:7]
	v_mfma_f32_16x16x32_bf16 v[0:3], v[212:215], v[170:173], v[0:3]
	s_waitcnt vmcnt(0)
	v_mfma_f32_16x16x32_bf16 v[12:15], v[122:125], v[90:93], v[12:15]
	v_mfma_f32_16x16x32_bf16 v[8:11], v[216:219], v[90:93], v[8:11]
	v_mfma_f32_16x16x32_bf16 v[4:7], v[122:125], v[236:239], v[4:7]
	v_mfma_f32_16x16x32_bf16 v[0:3], v[216:219], v[236:239], v[0:3]
	s_nop 1
	s_lshl_b32 s3, s2, 1
	s_lshl_b32 s4, s2, 7
	s_andn2_b32 s3, s3, 63
	s_and_b32 s4, s4, 0xf80
	v_or_b32_e32 v22, s4, v58
	v_add_u32_e32 v20, s3, v59
	v_max_f32_e32 v8, v8, v8
	v_ashrrev_i32_e32 v21, 31, v20
	v_lshlrev_b32_e32 v148, 1, v22
	v_max_f32_e32 v8, 0, v8
	v_max_f32_e32 v9, v9, v9
	v_lshl_add_u64 v[22:23], v[16:17], 0, v[148:149]
	v_lshlrev_b64 v[24:25], 13, v[20:21]
	v_mul_f32_e32 v8, v8, v8
	v_max_f32_e32 v9, 0, v9
	v_max_f32_e32 v10, v10, v10
	v_max_f32_e32 v11, v11, v11
	v_lshl_add_u64 v[24:25], v[22:23], 0, v[24:25]
	v_mul_f32_e32 v9, v9, v9
	v_max_f32_e32 v10, 0, v10
	v_max_f32_e32 v11, 0, v11
	v_cvt_pk_bf16_f32 v8, v8, v9
	v_mul_f32_e32 v10, v10, v10
	v_mul_f32_e32 v11, v11, v11
	v_cvt_pk_bf16_f32 v9, v10, v11
	global_store_dwordx2 v[24:25], v[8:9], off offset:32
	v_or_b32_e32 v8, 16, v20
	v_max_f32_e32 v12, v12, v12
	v_max_f32_e32 v13, v13, v13
	v_ashrrev_i32_e32 v9, 31, v8
	v_max_f32_e32 v4, v4, v4
	v_max_f32_e32 v5, v5, v5
	v_max_f32_e32 v0, v0, v0
	v_max_f32_e32 v1, v1, v1
	v_max_f32_e32 v12, 0, v12
	v_max_f32_e32 v13, 0, v13
	v_max_f32_e32 v14, v14, v14
	v_max_f32_e32 v15, v15, v15
	v_lshlrev_b64 v[8:9], 13, v[8:9]
	v_max_f32_e32 v4, 0, v4
	v_max_f32_e32 v5, 0, v5
	v_max_f32_e32 v6, v6, v6
	v_max_f32_e32 v7, v7, v7
	v_max_f32_e32 v0, 0, v0
	v_max_f32_e32 v1, 0, v1
	v_max_f32_e32 v2, v2, v2
	v_max_f32_e32 v3, v3, v3
	s_add_i32 s2, s2, s86
	s_add_i32 s1, s1, s5
	s_add_i32 s0, s0, s8
	v_mul_f32_e32 v12, v12, v12
	v_mul_f32_e32 v13, v13, v13
	v_max_f32_e32 v14, 0, v14
	v_max_f32_e32 v15, 0, v15
	v_lshl_add_u64 v[8:9], v[22:23], 0, v[8:9]
	v_mul_f32_e32 v4, v4, v4
	v_mul_f32_e32 v5, v5, v5
	v_max_f32_e32 v6, 0, v6
	v_max_f32_e32 v7, 0, v7
	v_mul_f32_e32 v0, v0, v0
	v_mul_f32_e32 v1, v1, v1
	v_max_f32_e32 v2, 0, v2
	v_max_f32_e32 v3, 0, v3
	s_cmpk_gt_i32 s2, 0xff
	v_mul_f32_e32 v14, v14, v14
	v_mul_f32_e32 v15, v15, v15
	v_cvt_pk_bf16_f32 v12, v12, v13
	v_cvt_pk_bf16_f32 v13, v14, v15
	global_store_dwordx2 v[24:25], v[12:13], off
	v_mul_f32_e32 v6, v6, v6
	v_mul_f32_e32 v7, v7, v7
	v_cvt_pk_bf16_f32 v4, v4, v5
	v_cvt_pk_bf16_f32 v5, v6, v7
	global_store_dwordx2 v[8:9], v[4:5], off
	v_mul_f32_e32 v2, v2, v2
	v_mul_f32_e32 v3, v3, v3
	v_cvt_pk_bf16_f32 v0, v0, v1
	v_cvt_pk_bf16_f32 v1, v2, v3
	global_store_dwordx2 v[8:9], v[0:1], off offset:32
	s_cbranch_scc0 .LBB0_712
